# v26 + phase-0 x-row sum-of-squares reduction via DPP/permlane swaps (bit-exact)
# speedup vs baseline: 1.0005x; 1.0005x over previous
; __device__ __forceinline__ unsigned cvtpk(float lo, float hi) { unsigned r; asm volatile("v_cvt_pk_bf16_f32 %0, %1, %2" : "=v"(r) : "v"(lo), "v"(hi)); return r; }
; __device__ __forceinline__ void phase0(KArgs a, LAS unsigned char* lds, int gw, int NGW, int wave, int lane) {
;     ...
;         {
;             const float* src = r < MPROMPT ? a->in[I_XP] + (size_t)r * DM : a->in[I_XS] + (size_t)(r - MPROMPT) * DM;
;             float* X = (float*)(ws + WS_X) + (size_t)r * DM; bf16* XB = (bf16*)(ws + WS_XB) + (size_t)r * DM; float ss = 0.f;
; #pragma unroll
;             for (int j = 0; j < 4; ++j) { const int c = j * 512 + lane * 8; f32x4 v0 = (f32x4){0.f, 0.f, 0.f, 0.f}, v1 = v0;
;                 if (r < MREAL) { v0 = *(const f32x4*)(src + c); v1 = *(const f32x4*)(src + c + 4); }
;                 if (r >= MPROMPT) { *(f32x4*)(X + c) = v0; *(f32x4*)(X + c + 4) = v1; }
;                 ss += (v0[0] * v0[0] + v0[1] * v0[1]) + (v0[2] * v0[2] + v0[3] * v0[3]) + (v1[0] * v1[0] + v1[1] * v1[1]) + (v1[2] * v1[2] + v1[3] * v1[3]);
;                 u32x4 o; o.x = cvtpk(v0[0], v0[1]); o.y = cvtpk(v0[2], v0[3]); o.z = cvtpk(v1[0], v1[1]); o.w = cvtpk(v1[2], v1[3]); *(u32x4*)(XB + c) = o; }
;             ss = wave_sum(ss);
;             if (lane < 32) ((float*)(ws + WS_SS))[(size_t)lane * MPAD + r] = lane == 0 ? ss : 0.f;
;             if (lane == 0) ((float*)(ws + WS_RSTD))[r] = 1.0f / sqrtf(ss * (1.0f / 2048.0f) + RMS_EPS);
;         }
.LBB0_49:
	v_mul_f32_e32 v1, v1, v1
	v_fmac_f32_e32 v1, v0, v0
	v_mul_f32_e32 v0, v3, v3
	v_fmac_f32_e32 v0, v2, v2
	v_add_f32_e32 v0, v1, v0
	v_mul_f32_e32 v1, v5, v5
	v_fmac_f32_e32 v1, v4, v4
	v_add_f32_e32 v0, v0, v1
	v_mul_f32_e32 v1, v7, v7
	v_fmac_f32_e32 v1, v6, v6
	v_add_f32_e32 v0, v1, v0
	v_mul_f32_e32 v1, v9, v9
	v_mul_f32_e32 v2, v11, v11
	v_fmac_f32_e32 v1, v8, v8
	v_fmac_f32_e32 v2, v10, v10
	v_add_f32_e32 v1, v1, v2
	v_mul_f32_e32 v2, v13, v13
	v_fmac_f32_e32 v2, v12, v12
	v_add_f32_e32 v1, v1, v2
	v_mul_f32_e32 v2, v15, v15
	v_fmac_f32_e32 v2, v14, v14
	v_add_f32_e32 v1, v2, v1
	v_add_f32_e32 v0, v0, v1
	v_mul_f32_e32 v1, v21, v21
	v_mul_f32_e32 v2, v23, v23
	v_fmac_f32_e32 v1, v20, v20
	v_fmac_f32_e32 v2, v22, v22
	v_add_f32_e32 v1, v1, v2
	v_mul_f32_e32 v2, v29, v29
	v_fmac_f32_e32 v2, v28, v28
	v_add_f32_e32 v1, v1, v2
	v_mul_f32_e32 v2, v31, v31
	v_fmac_f32_e32 v2, v30, v30
	v_add_f32_e32 v1, v2, v1
	v_add_f32_e32 v0, v0, v1
	s_waitcnt vmcnt(1)
	v_mul_f32_e32 v1, v17, v17
	v_mul_f32_e32 v2, v19, v19
	v_fmac_f32_e32 v1, v16, v16
	v_fmac_f32_e32 v2, v18, v18
	v_add_f32_e32 v1, v1, v2
	s_waitcnt vmcnt(0)
	v_mul_f32_e32 v2, v25, v25
	v_fmac_f32_e32 v2, v24, v24
	v_add_f32_e32 v1, v1, v2
	v_mul_f32_e32 v2, v27, v27
	v_fmac_f32_e32 v2, v26, v26
	v_add_f32_e32 v1, v2, v1
	v_add_f32_e32 v0, v0, v1
	v_and_b32_e32 v1, 64, v131
	v_add_u32_e32 v1, 64, v1
	v_xor_b32_e32 v2, 1, v131
	v_cmp_lt_i32_e32 vcc, v2, v1
	s_nop 1
	v_cndmask_b32_e32 v2, v131, v2, vcc
	v_lshlrev_b32_e32 v2, 2, v2
	s_nop 1
	v_add_f32_dpp v2, v0, v0 quad_perm:[1,0,3,2] row_mask:0xf bank_mask:0xf
	s_waitcnt lgkmcnt(0)
	v_mov_b32_e32 v0, v2
	v_xor_b32_e32 v2, 2, v131
	v_cmp_lt_i32_e32 vcc, v2, v1
	s_nop 1
	v_cndmask_b32_e32 v2, v131, v2, vcc
	v_lshlrev_b32_e32 v2, 2, v2
	s_nop 1
	v_add_f32_dpp v2, v0, v0 quad_perm:[2,3,0,1] row_mask:0xf bank_mask:0xf
	s_waitcnt lgkmcnt(0)
	v_mov_b32_e32 v0, v2
	v_xor_b32_e32 v2, 4, v131
	v_cmp_lt_i32_e32 vcc, v2, v1
	s_nop 1
	v_cndmask_b32_e32 v2, v131, v2, vcc
	v_lshlrev_b32_e32 v2, 2, v2
	s_nop 1
	v_add_f32_dpp v2, v0, v0 row_half_mirror row_mask:0xf bank_mask:0xf
	s_waitcnt lgkmcnt(0)
	v_mov_b32_e32 v0, v2
	v_xor_b32_e32 v2, 8, v131
	v_cmp_lt_i32_e32 vcc, v2, v1
	s_nop 1
	v_cndmask_b32_e32 v2, v131, v2, vcc
	v_lshlrev_b32_e32 v2, 2, v2
	s_nop 1
	v_add_f32_dpp v2, v0, v0 row_mirror row_mask:0xf bank_mask:0xf
	s_waitcnt lgkmcnt(0)
	v_xor_b32_e32 v0, 16, v131
	v_cmp_lt_i32_e32 vcc, v0, v1
	s_nop 1
	v_cndmask_b32_e32 v0, v131, v0, vcc
	v_lshlrev_b32_e32 v0, 2, v0
	v_mov_b32_e32 v3, v2
	v_mov_b32_e32 v170, v2
	s_nop 1
	v_permlane16_swap_b32_e32 v3, v170
	v_cvt_pk_bf16_f32 v0, v16, v17
	s_waitcnt lgkmcnt(0)
	v_add_f32_e32 v4, v3, v170
	v_xor_b32_e32 v2, 32, v131
	v_cmp_lt_i32_e32 vcc, v2, v1
	s_nop 1
	v_cndmask_b32_e32 v1, v131, v2, vcc
	v_lshlrev_b32_e32 v1, 2, v1
	v_mov_b32_e32 v5, v4
	v_mov_b32_e32 v170, v4
	s_nop 1
	v_permlane32_swap_b32_e32 v5, v170
	v_cvt_pk_bf16_f32 v1, v18, v19
	v_cvt_pk_bf16_f32 v2, v24, v25
	v_cvt_pk_bf16_f32 v3, v26, v27
	global_store_dwordx4 v[32:33], v[0:3], off offset:3072
	s_waitcnt lgkmcnt(0)
	s_nop 0
	v_add_f32_e32 v0, v5, v170
	s_and_saveexec_b64 s[8:9], s[4:5]
	s_cbranch_execz .LBB0_51
	v_lshl_add_u64 v[2:3], s[40:41], 2, v[68:69]
	v_cndmask_b32_e64 v1, 0, v0, s[6:7]
	global_store_dword v[2:3], v1, off
